# setup phase: waves 4-7 of each workgroup run the bandwidth-bound tasks (weight transposes, x conversion) first and the latency-bound table builders second, waves 0-3 the reverse, so both overlap
# speedup vs baseline: 1.0031x; 1.0031x over previous
; __global__ void __launch_bounds__(NTHR, 2) fwd_megakernel(Args kargs) {
;     ...
;     PH_BEGIN
;       for (int rep = 0; rep < DUP_P0; ++rep) {
;     ...
;         ssm_tables1(a, gt, NGT);
;         attn_table(a, gt, NGT);
;         wcat_fold(a, gt, NGT);
;         transposes_phase(a, (LAS float*)(lds + wave * 8448), gw, NGW, lane);
;     ...
;         rowwise_phase(a->x, HB, nullptr, nullptr, 0.f, RS, nullptr, gw, NGW, lane);
.LBB0_74:
	s_mov_b32 s101, 0
	s_lshl_b32 s38, s50, 3
	s_cmp_lt_i32 s86, 2
	s_cselect_b64 s[12:13], -1, 0
	s_and_b64 s[0:1], s[12:13], s[4:5]
	s_andn2_b64 vcc, exec, s[0:1]
	s_cbranch_vccnz .LBB0_253
.Lp0_again:
	s_mov_b64 s[14:15], s[82:83]
	v_mov_b32_e32 v34, v202
	s_load_dwordx2 s[16:17], s[14:15], 0xb8
	v_lshl_add_u32 v6, s2, 9, v34
	s_mov_b32 s0, 0x100000
	v_readfirstlane_b32 s3, v34
	s_cmp_lg_u32 s101, 0
	s_cbranch_scc1 .Lp0_h1_skip
	s_nop 3
	s_cmp_lt_u32 s3, 0x100
	s_cbranch_scc1 .Lp0_h1_skip
	s_mov_b32 s101, 1
	s_mov_b64 s[0:1], exec
	s_branch .LBB0_105
.Lp0_h1_skip:
	v_cmp_gt_i32_e32 vcc, s0, v6
	s_and_saveexec_b64 s[0:1], vcc
	s_cbranch_execz .LBB0_100
	s_load_dwordx4 s[8:11], s[14:15], 0x68
	s_waitcnt lgkmcnt(0)
	s_add_u32 s4, s16, 0x36200000
	v_and_b32_e32 v1, 15, v34
	v_lshlrev_b32_e32 v3, 2, v34
	s_addc_u32 s5, s17, 0
	v_lshlrev_b32_e32 v2, 3, v1
	v_mov_b32_e32 v5, 0
	v_lshl_add_u32 v3, s2, 11, v3
	s_lshl_b32 s26, s50, 11
	s_mov_b64 s[6:7], 0
	s_movk_i32 s27, 0xf00
	s_mov_b64 s[18:19], 0x35d00000
	s_mov_b64 s[22:23], 0x200
	s_mov_b32 s28, 0xfffff
	v_mov_b32_e32 v8, v6

; __device__ __forceinline__ TItem titem_decode(ArgsP a, int it) {
;     constexpr int I_FFN = 4224, N_FFN = 8 * I_FFN, I_MIX = 2944;
;     const float* W; int ldw, nblk, ldt, orow_add = 0, r; bf16_t* WT; float scale = 1.f; bool il = false; const float* gk = nullptr;
;     if (it < N_FFN) { const int f = it / I_FFN; r = it % I_FFN; const int which = r / 1408; r = r % 1408; if (which < 2) gk = a->norm_g + (size_t)((f >> 1) * 6 + ((f & 1) ? 4 : 0)) * DM;
;         if (which == 0) { W = a->w_gate + (size_t)f * DM * DFF; ldw = DFF; nblk = 88; WT = (bf16_t*)(a->ws + WS_WGU + f * SZ_WGU); ldt = DM; il = true; }
;         else if (which == 1) { W = a->w_up + (size_t)f * DM * DFF; ldw = DFF; nblk = 88; WT = (bf16_t*)(a->ws + WS_WGU + f * SZ_WGU); ldt = DM; il = true; orow_add = 128; }
;         else { W = a->w_down + (size_t)f * DFF * DM; ldw = DM; nblk = 32; WT = (bf16_t*)(a->ws + WS_WD + f * SZ_WD); ldt = DFF; }
;     } else { const int it2 = it - N_FFN, i = it2 / I_MIX; r = it2 % I_MIX;
;         if (r < 512) { gk = a->norm_g + (size_t)((2 * i) * 6 + 2) * DM; W = a->ab_w_in + (size_t)i * DM * DM; ldw = DM; nblk = 32; WT = (bf16_t*)(a->ws + WS_WIN) + (size_t)i * DM * DM; ldt = DM; }
;         else if (r < 768) { r -= 512; W = a->ab_w_out + (size_t)i * DM * DM + (size_t)512 * DM; ldw = DM; nblk = 32; WT = (bf16_t*)(a->ws + WS_WCAT) + (size_t)i * DM * DM + 512; ldt = DM; }
;         else if (r < 896) { r -= 768; W = a->w_glu + (size_t)i * 512 * 512; ldw = 512; nblk = 16; WT = (bf16_t*)(a->ws + WS_WGLU) + (size_t)i * 512 * 512; ldt = 512; }
;         else if (r < 2432) { r -= 896; gk = a->norm_g + (size_t)((2 * i + 1) * 6 + 2) * DM; W = a->w_qkv + (size_t)i * DM * 3072; ldw = 3072; nblk = 96; WT = (bf16_t*)(a->ws + WS_WQKV) + (size_t)i * 3072 * DM; ldt = DM; if ((r % 96) < 32) scale = 0.125f * 1.4426950408889634f;     }
; __device__ __forceinline__ void transposes_phase(ArgsP a, LAS float* scr, int gw, int NGW, int lane) {
;     constexpr int N_ALL = 8 * 4224 + 2 * 2944;
;     if (gw >= N_ALL) return;
;     TItem cur = titem_decode(a, gw); f32x4 v[8]; float gm[8]; tile_load(cur, lane, v, gm);
;     for (int it = gw; it < N_ALL; it += NGW) {
;         const int nx = it + NGW; const bool has = nx < N_ALL; TItem nxt = cur; f32x4 vn[8]; float gn[8];
;         if (has) { nxt = titem_decode(a, nx); tile_load(nxt, lane, vn, gn); }
.LBB0_105:
	s_or_b64 exec, exec, s[0:1]
	s_cmp_eq_u32 s101, 2
	s_cbranch_scc1 .LBB0_253
	s_ashr_i32 s30, s3, 6
	s_lshl_b32 s0, s2, 3
	s_add_i32 s8, s30, s0
	s_cmp_gt_i32 s8, 0x9aff
	v_and_b32_e32 v1, 63, v34
	s_cbranch_scc1 .LBB0_210
	s_waitcnt lgkmcnt(0)
	s_add_u32 s3, s16, 0x31900000
	s_addc_u32 s9, s17, 0
	s_add_u32 s33, s16, 0x30d00000
	s_addc_u32 s42, s17, 0
	s_add_u32 s43, s16, 0x30c00000
	s_addc_u32 s44, s17, 0
	s_add_u32 s45, s16, 0x30400000
	s_addc_u32 s46, s17, 0
	s_add_u32 s47, s16, 0x2d800000
	s_addc_u32 s52, s17, 0
	s_add_u32 s53, s16, 0x28000000
	s_addc_u32 s56, s17, 0
	s_mov_b32 s64, s38
	s_cmp_gt_i32 s8, 0x83ff
	s_cbranch_scc0 .LBB0_112
	s_add_i32 s0, s8, 0xffff7c00
	s_cmpk_gt_u32 s0, 0xb7f
	s_cselect_b64 s[4:5], -1, 0
	s_add_i32 s1, s8, 0xffff7080
	s_cmpk_lt_u32 s0, 0xb80
	s_cselect_b32 s24, s0, s1
	v_mov_b32_e32 v2, 0x200
	v_sub_co_u32_e32 v2, vcc, s24, v2
	s_and_b64 s[0:1], s[4:5], exec
	s_cselect_b32 s25, 0x100000, 0
	s_andn2_b64 vcc, exec, vcc
	v_readfirstlane_b32 s26, v2
	s_cbranch_vccz .LBB0_114
	v_mov_b32_e32 v2, 0x300
	v_sub_co_u32_e32 v2, vcc, s24, v2
	s_andn2_b64 vcc, exec, vcc
	v_readfirstlane_b32 s0, v2
	s_cbranch_vccz .LBB0_115
	v_mov_b32_e32 v2, 0x380
	v_sub_co_u32_e32 v2, vcc, s24, v2
	s_andn2_b64 vcc, exec, vcc
	v_readfirstlane_b32 s10, v2
	s_cbranch_vccz .LBB0_116
	v_mov_b32_e32 v2, 0x980
	v_sub_co_u32_e32 v2, vcc, s24, v2
	s_andn2_b64 vcc, exec, vcc
	v_readfirstlane_b32 s26, v2
	s_cbranch_vccz .LBB0_117
	s_load_dwordx2 s[6:7], s[14:15], 0xa8
	s_lshl_b32 s0, s25, 1
	s_add_u32 s0, s3, s0
	s_addc_u32 s1, s9, 0
	s_lshl_b32 s11, s25, 2
	s_waitcnt lgkmcnt(0)
	s_add_u32 s18, s6, s11
	s_addc_u32 s19, s7, 0
	s_mov_b64 s[6:7], 0
	s_branch .LBB0_118

; #define PH_END } { const bool seam = (ph >= lo && ph + 1 < hi); ++ph; if (seam) for (int rs = 0; rs < DUP_SYNC; ++rs) { if (ph == 2) grid.sync(); else xcd_barrier(xbar); } }
; __global__ void __launch_bounds__(NTHR, 2) fwd_megakernel(Args kargs) {
;     ...
;       for (int rep = 0; rep < DUP_P0; ++rep) {
;     ...
;         ssm_tables1(a, gt, NGT);
;         attn_table(a, gt, NGT);
;         wcat_fold(a, gt, NGT);
;         transposes_phase(a, (LAS float*)(lds + wave * 8448), gw, NGW, lane);
;     ...
;         rowwise_phase(a->x, HB, nullptr, nullptr, 0.f, RS, nullptr, gw, NGW, lane);
;       }
;     PH_END
.LBB0_253:
	s_cmp_eq_u32 s101, 1
	s_cbranch_scc0 .Lp0_h3_skip
	s_mov_b32 s101, 2
	s_branch .Lp0_again
